# row-group (4-workgroup, same-XCD) barriers replace the grid barrier at P4->P5 and P11->P12, guarded by the run-time XCC check
# speedup vs baseline: 1.0578x; 1.0061x over previous
.LBB0_709:
	s_cmp_gt_i32 s89, 5
	s_cselect_b64 s[4:5], -1, 0
	s_and_b64 s[6:7], s[6:7], s[4:5]
	s_andn2_b64 vcc, exec, s[6:7]
	s_cbranch_vccnz .LBB0_763
	s_waitcnt vmcnt(0)
	s_waitcnt vmcnt(0)
	s_barrier
	s_and_saveexec_b64 s[6:7], s[26:27]
	s_cbranch_execz .LBB0_762
	s_cmp_eq_u32 s100, 0
	s_cbranch_scc1 .Lgrp_full_4
	s_and_b32 s98, s2, 63
	s_lshl_b32 s98, s98, 2
	v_mov_b32_e32 v0, s98
	v_mov_b32_e32 v1, 1
	global_atomic_add v0, v1, s[34:35]
	s_mov_b32 s99, 0
.Lgrp_spin_4:
	global_load_dword v2, v0, s[34:35] sc1
	s_waitcnt vmcnt(0)
	v_readfirstlane_b32 s101, v2
	s_nop 3
	s_cmp_ge_u32 s101, 4
	s_cbranch_scc1 .Lgrp_rel_4
	s_sleep 1
	s_add_u32 s99, s99, 1
	s_cmp_lt_u32 s99, 0x40000
	s_cbranch_scc1 .Lgrp_spin_4
.Lgrp_rel_4:
	buffer_inv sc1
	s_waitcnt vmcnt(0)
	s_branch .LBB0_762
.Lgrp_full_4:
	s_add_i32 s8, 0, 0x22020
	v_mov_b32_e32 v0, s8
	s_waitcnt vmcnt(0) expcnt(0) lgkmcnt(0)
	ds_read_b32 v2, v0
	s_add_i32 s8, 0, 0x22024
	v_mov_b32_e32 v0, s8
	ds_read_b32 v0, v0
	s_waitcnt lgkmcnt(1)
	v_cmp_ne_u32_e32 vcc, 0, v2
	s_cbranch_vccnz .LBB0_726
	s_add_u32 s8, s30, 0x40200
	s_addc_u32 s9, s31, 0
	s_add_u32 s10, s30, 0x40400
	s_addc_u32 s11, s31, 0
	s_add_u32 s12, s30, 0x40500
	s_addc_u32 s13, s31, 0
	s_add_u32 s14, s30, 0x40600
	s_addc_u32 s15, s31, 0
	s_add_u32 s16, s30, 0x40700
	s_addc_u32 s17, s31, 0
	s_add_u32 s18, s30, 0x40800
	s_addc_u32 s19, s31, 0
	s_add_u32 s20, s30, 0x40900
	s_addc_u32 s21, s31, 0
	s_add_u32 s22, s30, 0x40a00
	s_addc_u32 s23, s31, 0
	s_add_u32 s24, s30, 0x40b00
	s_addc_u32 s25, s31, 0
	s_add_u32 s36, s30, 0x40c00
	s_addc_u32 s37, s31, 0
	s_add_u32 s38, s30, 0x40d00
	s_addc_u32 s39, s31, 0
	s_add_u32 s40, s30, 0x40e00
	s_addc_u32 s41, s31, 0
	s_add_u32 s42, s30, 0x40f00
	s_addc_u32 s43, s31, 0
	s_add_u32 s44, s30, 0x41000
	s_addc_u32 s45, s31, 0
	s_add_u32 s46, s30, 0x41100
	s_addc_u32 s47, s31, 0
	s_add_u32 s48, s30, 0x41200
	s_addc_u32 s49, s31, 0
	s_mul_i32 s58, s29, s90
	s_add_u32 s50, s30, 0x41300
	s_mul_i32 s58, s58, s28
	s_addc_u32 s51, s31, 0
	s_mov_b32 s59, 1
	v_mov_b32_e32 v16, 0
	s_branch .LBB0_714

.LBB0_1329:
	s_cmp_gt_i32 s89, 12
	s_cselect_b64 s[4:5], -1, 0
	s_and_b64 s[6:7], s[6:7], s[4:5]
	s_andn2_b64 vcc, exec, s[6:7]
	s_cbranch_vccnz .LBB0_1383
	s_waitcnt vmcnt(0)
	s_waitcnt vmcnt(0)
	s_barrier
	s_and_saveexec_b64 s[6:7], s[26:27]
	s_cbranch_execz .LBB0_1382
	s_cmp_eq_u32 s100, 0
	s_cbranch_scc1 .Lgrp_full_11
	s_and_b32 s98, s2, 63
	s_lshl_b32 s98, s98, 2
	v_mov_b32_e32 v0, s98
	v_mov_b32_e32 v1, 1
	global_atomic_add v0, v1, s[34:35]
	s_mov_b32 s99, 0
.Lgrp_spin_11:
	global_load_dword v2, v0, s[34:35] sc1
	s_waitcnt vmcnt(0)
	v_readfirstlane_b32 s101, v2
	s_nop 3
	s_cmp_ge_u32 s101, 8
	s_cbranch_scc1 .Lgrp_rel_11
	s_sleep 1
	s_add_u32 s99, s99, 1
	s_cmp_lt_u32 s99, 0x40000
	s_cbranch_scc1 .Lgrp_spin_11

.Lgrp_full_11:
	s_add_i32 s8, 0, 0x22020
	v_mov_b32_e32 v0, s8
	s_waitcnt vmcnt(0) expcnt(0) lgkmcnt(0)
	ds_read_b32 v2, v0
	s_add_i32 s8, 0, 0x22024
	v_mov_b32_e32 v0, s8
	ds_read_b32 v0, v0
	s_waitcnt lgkmcnt(1)
	v_cmp_ne_u32_e32 vcc, 0, v2
	s_cbranch_vccnz .LBB0_1346
	s_add_u32 s8, s30, 0x40200
	s_addc_u32 s9, s31, 0
	s_add_u32 s10, s30, 0x40400
	s_addc_u32 s11, s31, 0
	s_add_u32 s12, s30, 0x40500
	s_addc_u32 s13, s31, 0
	s_add_u32 s14, s30, 0x40600
	s_addc_u32 s15, s31, 0
	s_add_u32 s16, s30, 0x40700
	s_addc_u32 s17, s31, 0
	s_add_u32 s18, s30, 0x40800
	s_addc_u32 s19, s31, 0
	s_add_u32 s20, s30, 0x40900
	s_addc_u32 s21, s31, 0
	s_add_u32 s22, s30, 0x40a00
	s_addc_u32 s23, s31, 0
	s_add_u32 s24, s30, 0x40b00
	s_addc_u32 s25, s31, 0
	s_add_u32 s26, s30, 0x40c00
	s_addc_u32 s27, s31, 0
	s_add_u32 s36, s30, 0x40d00
	s_addc_u32 s37, s31, 0
	s_add_u32 s38, s30, 0x40e00
	s_addc_u32 s39, s31, 0
	s_add_u32 s40, s30, 0x40f00
	s_addc_u32 s41, s31, 0
	s_add_u32 s42, s30, 0x41000
	s_addc_u32 s43, s31, 0
	s_add_u32 s44, s30, 0x41100
	s_addc_u32 s45, s31, 0
	s_add_u32 s46, s30, 0x41200
	s_addc_u32 s47, s31, 0
	s_mul_i32 s29, s29, s90
	s_add_u32 s48, s30, 0x41300
	s_mul_i32 s29, s29, s28
	s_addc_u32 s49, s31, 0
	s_mov_b32 s56, 1
	v_mov_b32_e32 v16, 0
	s_branch .LBB0_1334
